# attention unmasked loop: K and V LDS fragment reads issued 7 MFMAs ahead of their consumers (register tuple rotation)
# baseline (speedup 1.0000x reference)
.LBB0_581:
	s_setprio 1
	s_bitcmp1_b32 s4, 0
	s_cselect_b32 s30, 0x4400, 0
	v_add_u32_e32 v0, s30, v224
	s_mul_i32 s30, s6, 0x5000
	ds_read_b128 v[2:5], v0
	ds_read_b128 v[6:9], v0 offset:8704
	v_add_u32_e32 v21, s30, v225
	ds_read_b128 v[10:13], v0 offset:32
	ds_read_b128 v[28:31], v0 offset:8736
	ds_read_b128 v[236:239], v0 offset:64
	ds_read_b128 v[240:243], v0 offset:8768
	ds_read_b128 v[24:27], v0 offset:96
	s_waitcnt lgkmcnt(6)
	v_mfma_f32_32x32x16_bf16 v[128:143], v[2:5], v[144:147], v[96:111]
	ds_read_b128 v[2:5], v0 offset:8800
	s_waitcnt lgkmcnt(6)
	v_mfma_f32_32x32x16_bf16 v[112:127], v[6:9], v[144:147], v[96:111]
	ds_read_b64_tr_b16 v[6:7], v21 offset:34816
	ds_read_b64_tr_b16 v[8:9], v21 offset:37376
	s_waitcnt lgkmcnt(7)
	v_mfma_f32_32x32x16_bf16 v[128:143], v[10:13], v[148:151], v[128:143]
	ds_read_b64_tr_b16 v[10:11], v21 offset:34880
	ds_read_b64_tr_b16 v[12:13], v21 offset:37440
	s_waitcnt lgkmcnt(8)
	v_mfma_f32_32x32x16_bf16 v[112:127], v[28:31], v[148:151], v[112:127]
	ds_read_b64_tr_b16 v[28:29], v21 offset:34944
	ds_read_b64_tr_b16 v[30:31], v21 offset:37504
	s_waitcnt lgkmcnt(9)
	v_mfma_f32_32x32x16_bf16 v[128:143], v[236:239], v[152:155], v[128:143]
	ds_read_b64_tr_b16 v[236:237], v21 offset:35008
	ds_read_b64_tr_b16 v[238:239], v21 offset:37568
	s_waitcnt lgkmcnt(10)
	v_mfma_f32_32x32x16_bf16 v[112:127], v[240:243], v[152:155], v[112:127]
	ds_read_b64_tr_b16 v[240:241], v21 offset:39936
	ds_read_b64_tr_b16 v[242:243], v21 offset:42496
	s_waitcnt lgkmcnt(11)
	v_mfma_f32_32x32x16_bf16 v[128:143], v[24:27], v[156:159], v[128:143]
	ds_read_b64_tr_b16 v[24:25], v21 offset:40000
	ds_read_b64_tr_b16 v[26:27], v21 offset:42560
	s_waitcnt lgkmcnt(12)
	v_mfma_f32_32x32x16_bf16 v[112:127], v[2:5], v[156:159], v[112:127]
	ds_read_b64_tr_b16 v[2:3], v21 offset:40064
	ds_read_b64_tr_b16 v[4:5], v21 offset:42624
	s_waitcnt lgkmcnt(12)
	v_mfma_f32_32x32x16_bf16 v[64:79], v[188:191], v[6:9], v[64:79]
	ds_read_b64_tr_b16 v[6:7], v21 offset:40128
	ds_read_b64_tr_b16 v[8:9], v21 offset:42688
	s_nop 1
	v_exp_f32_e32 v128, v128
	v_exp_f32_e32 v129, v129
	v_exp_f32_e32 v130, v130
	v_add_f32_e32 v17, v128, v129
	s_waitcnt lgkmcnt(12)
	v_mfma_f32_32x32x16_bf16 v[80:95], v[188:191], v[10:13], v[80:95]
	ds_read_b64_tr_b16 v[10:11], v21 offset:45056
	ds_read_b64_tr_b16 v[12:13], v21 offset:47616
	v_exp_f32_e32 v131, v131
	v_exp_f32_e32 v132, v132
	v_exp_f32_e32 v133, v133
	v_add_f32_e32 v17, v17, v130
	s_waitcnt lgkmcnt(12)
	v_mfma_f32_32x32x16_bf16 v[48:63], v[188:191], v[28:31], v[48:63]
	ds_read_b64_tr_b16 v[28:29], v21 offset:45120
	ds_read_b64_tr_b16 v[30:31], v21 offset:47680
	v_exp_f32_e32 v134, v134
	v_exp_f32_e32 v135, v135
	v_exp_f32_e32 v136, v136
	v_add_f32_e32 v17, v17, v131
	s_waitcnt lgkmcnt(12)
	v_mfma_f32_32x32x16_bf16 v[32:47], v[188:191], v[236:239], v[32:47]
	ds_read_b64_tr_b16 v[236:237], v21 offset:45184
	ds_read_b64_tr_b16 v[238:239], v21 offset:47744
	v_exp_f32_e32 v137, v137
	v_exp_f32_e32 v138, v138
	v_exp_f32_e32 v139, v139
	v_cvt_pk_bf16_f32 v188, v128, v129
	s_waitcnt lgkmcnt(12)
	v_mfma_f32_32x32x16_bf16 v[64:79], v[184:187], v[240:243], v[64:79]
	ds_read_b64_tr_b16 v[240:241], v21 offset:45248
	ds_read_b64_tr_b16 v[242:243], v21 offset:47808
	v_exp_f32_e32 v140, v140
	v_exp_f32_e32 v141, v141
	v_exp_f32_e32 v142, v142
	v_cvt_pk_bf16_f32 v189, v130, v131
	s_waitcnt lgkmcnt(12)
	v_mfma_f32_32x32x16_bf16 v[80:95], v[184:187], v[24:27], v[80:95]
	ds_read_b64_tr_b16 v[24:25], v21 offset:50176
	ds_read_b64_tr_b16 v[26:27], v21 offset:52736
	v_exp_f32_e32 v143, v143
	v_exp_f32_e32 v112, v112
	v_exp_f32_e32 v113, v113
	v_cvt_pk_bf16_f32 v190, v132, v133
	s_waitcnt lgkmcnt(12)
	v_mfma_f32_32x32x16_bf16 v[48:63], v[184:187], v[2:5], v[48:63]
	ds_read_b64_tr_b16 v[2:3], v21 offset:50240
	ds_read_b64_tr_b16 v[4:5], v21 offset:52800
	v_exp_f32_e32 v114, v114
	v_exp_f32_e32 v115, v115
	v_exp_f32_e32 v116, v116
	v_cvt_pk_bf16_f32 v191, v134, v135
	s_waitcnt lgkmcnt(12)
	v_mfma_f32_32x32x16_bf16 v[32:47], v[184:187], v[6:9], v[32:47]
	ds_read_b64_tr_b16 v[6:7], v21 offset:50304
	ds_read_b64_tr_b16 v[8:9], v21 offset:52864
	s_andn2_b32 s30, 1, s4
	s_mulk_i32 s30, 0x4400
	s_mul_i32 s31, s34, 0x5000
	v_add3_u32 v22, v223, s30, v228
	v_add3_u32 v23, v223, s31, v229
	v_exp_f32_e32 v117, v117
	v_exp_f32_e32 v118, v118
	v_exp_f32_e32 v119, v119
	v_cvt_pk_bf16_f32 v184, v136, v137
	s_waitcnt lgkmcnt(12)
	v_mfma_f32_32x32x16_bf16 v[64:79], v[180:183], v[10:13], v[64:79]
	ds_read_b64_tr_b16 v[10:11], v21 offset:50368
	ds_read_b64_tr_b16 v[12:13], v21 offset:52928
	s_waitcnt vmcnt(3)
	ds_write_b128 v22, v[160:163]
	v_exp_f32_e32 v120, v120
	v_exp_f32_e32 v121, v121
	v_exp_f32_e32 v122, v122
	v_cvt_pk_bf16_f32 v185, v138, v139
	s_waitcnt lgkmcnt(13)
	v_mfma_f32_32x32x16_bf16 v[80:95], v[180:183], v[28:31], v[80:95]
	s_waitcnt vmcnt(2)
	ds_write_b128 v23, v[164:167] offset:34816
	v_exp_f32_e32 v123, v123
	v_exp_f32_e32 v124, v124
	v_exp_f32_e32 v125, v125
	v_cvt_pk_bf16_f32 v186, v140, v141
	s_waitcnt lgkmcnt(12)
	v_mfma_f32_32x32x16_bf16 v[48:63], v[180:183], v[236:239], v[48:63]
	s_waitcnt vmcnt(1)
	ds_write_b128 v22, v[168:171] offset:8704
	v_exp_f32_e32 v126, v126
	v_exp_f32_e32 v127, v127
	v_cvt_pk_bf16_f32 v187, v142, v143
	v_add_f32_e32 v17, v17, v132
	v_add_f32_e32 v17, v17, v133
	s_waitcnt lgkmcnt(11)
	v_mfma_f32_32x32x16_bf16 v[32:47], v[180:183], v[240:243], v[32:47]
	s_waitcnt vmcnt(0)
	ds_write_b128 v23, v[172:175] offset:45056
	v_cvt_pk_bf16_f32 v180, v112, v113
	v_cvt_pk_bf16_f32 v181, v114, v115
	v_cvt_pk_bf16_f32 v182, v116, v117
	v_cvt_pk_bf16_f32 v183, v118, v119
	v_add_f32_e32 v17, v17, v134
	v_add_f32_e32 v17, v17, v135
	v_add_f32_e32 v18, v136, v137
	s_waitcnt lgkmcnt(10)
	v_mfma_f32_32x32x16_bf16 v[64:79], v[176:179], v[24:27], v[64:79]
	v_add_f32_e32 v18, v18, v138
	v_add_f32_e32 v18, v18, v139
	v_add_f32_e32 v18, v18, v140
	v_add_f32_e32 v18, v18, v141
	v_add_f32_e32 v18, v18, v142
	v_add_f32_e32 v18, v18, v143
	v_add_f32_e32 v19, v112, v113
	s_waitcnt lgkmcnt(8)
	v_mfma_f32_32x32x16_bf16 v[80:95], v[176:179], v[2:5], v[80:95]
	v_add_f32_e32 v19, v19, v114
	v_add_f32_e32 v19, v19, v115
	v_add_f32_e32 v19, v19, v116
	v_add_f32_e32 v19, v19, v117
	v_add_f32_e32 v19, v19, v118
	v_add_f32_e32 v19, v19, v119
	v_add_f32_e32 v20, v120, v121
	s_add_i32 s30, s4, 2
	s_cmp_ge_i32 s30, s27
	s_cbranch_scc1 .Lattn_u_skipld
	s_sub_i32 s30, s5, 32
	v_mad_u64_u32 v[22:23], s[30:31], s30, v219, v[202:203]
	global_load_dwordx4 v[160:163], v[22:23], off
	global_load_dwordx4 v[164:167], v[22:23], off offset:1024
	v_mad_u64_u32 v[22:23], s[30:31], s5, v219, v[202:203]
	global_load_dwordx4 v[168:171], v[22:23], off
	global_load_dwordx4 v[172:175], v[22:23], off offset:1024
; #define A_LOAD(t) do { _Pragma("unroll") for (int j_ = 0; j_ < 2; ++j_) { kreg[j_] = *(const u32x4*)(kg + (size_t)(64 * (t) + 32 * j_) * NIN); vreg[j_] = *(const u32x4*)(kg + 512 + (size_t)(64 * (t) + 32 * j_) * NIN); } } while (0)
; #define A_STORE(kbi, vbi) do { _Pragma("unroll") for (int j_ = 0; j_ < 2; ++j_) { *(LAS u32x4*)(lds + A_K0 + (kbi) * KBUF + (skey + 32 * j_) * KSTR + sch * 16) = kreg[j_]; *(LAS u32x4*)(lds + A_V0 + (vbi) * VBUF + (skey + 32 * j_) * VSTR + sch * 16) = vreg[j_]; } } while (0)
; __device__ __forceinline__ void attn_phase(LAS unsigned char* lds, const AttnArgs& a, int tid_in) {
;     ...
;             A_STORE((t + 1) & 1, vn);
;             if (t + 2 < NT) A_LOAD(t + 2);
;             __syncthreads();
;             vp = (vp == 2) ? 0 : vp + 1; vn = (vn == 2) ? 0 : vn + 1;
;         }
.Lattn_u_skipld:
	s_waitcnt lgkmcnt(6)
	v_mfma_f32_32x32x16_bf16 v[48:63], v[176:179], v[6:9], v[48:63]
	v_add_f32_e32 v20, v20, v122
	v_add_f32_e32 v20, v20, v123
	v_add_f32_e32 v20, v20, v124
	v_add_f32_e32 v20, v20, v125
	v_add_f32_e32 v20, v20, v126
	v_add_f32_e32 v20, v20, v127
	v_add_f32_e32 v17, v17, v18
	s_waitcnt lgkmcnt(4)
	v_mfma_f32_32x32x16_bf16 v[32:47], v[176:179], v[10:13], v[32:47]
	v_cvt_pk_bf16_f32 v176, v120, v121
	v_cvt_pk_bf16_f32 v177, v122, v123
	v_cvt_pk_bf16_f32 v178, v124, v125
	v_cvt_pk_bf16_f32 v179, v126, v127
	v_add_f32_e32 v19, v19, v20
	v_add_f32_e32 v17, v17, v19
	v_add_f32_e32 v211, v211, v17
	s_setprio 0
	s_add_i32 s30, s6, 1
	s_cmp_lg_u32 s6, 2
	s_cselect_b32 s6, s30, 0
	s_add_i32 s30, s34, 1
	s_cmp_lg_u32 s34, 2
	s_cselect_b32 s34, s30, 0
	s_add_i32 s4, s4, 1
	s_add_i32 s5, s5, 64
	s_cmp_eq_u32 s35, s4
	s_waitcnt lgkmcnt(0)
	s_barrier
	s_cbranch_scc0 .LBB0_581
	s_branch .LBB0_584
